# HM head-norm: half streamed in the idle time of the split barrier before attention, half inside attention items 0-1
# speedup vs baseline: 1.0048x; 1.0035x over previous
; __device__ __forceinline__ void st_wt16(void* p, u32x4 v) { asm volatile("global_store_dwordx4 %0, %1, off sc1\n\ts_nop 1" : : "v"(p), "v"(v) : "memory"); }
; __device__ __forceinline__ void p5_fixup(const Params& p) {
;     ...
;     for (int v0 = gtid; v0 < T_TOK * 128; v0 += 4 * gsz) {
;         u32x4 hv[4]; float4 s0[4], s1[4];
; #pragma unroll
;         for (int u = 0; u < 4; ++u) { const int v = v0 + u * gsz; if (v < T_TOK * 128) { const int row = v >> 7, head = (v >> 5) & 3;
;             hv[u] = __builtin_nontemporal_load((const u32x4*)(HM + (size_t)v * 8)); s0[u] = *(const float4*)(SSQ + ((size_t)row * 4 + head) * 8); s1[u] = *(const float4*)(SSQ + ((size_t)row * 4 + head) * 8 + 4); } }
; #pragma unroll
;         for (int u = 0; u < 4; ++u) { const int v = v0 + u * gsz; if (v < T_TOK * 128) {
;             const float ss = (s0[u].x + s0[u].y) + (s0[u].z + s0[u].w) + (s1[u].x + s1[u].y) + (s1[u].z + s1[u].w);
;             const float rstd = rsqrtf(ss * (1.0f / 256.0f) + EPS);
;             float f[8]; unpack8(hv[u], f);
; #pragma unroll
;             for (int e = 0; e < 8; ++e) f[e] *= rstd;
;             st_wt16(HM + (size_t)v * 8, pack8(f)); } }
.Lattn_perm_done:
	s_mov_b32 s99, 0
	s_cmp_lt_i32 s90, 6
	s_cselect_b64 s[0:1], -1, 0
	s_and_b64 s[96:97], s[0:1], s[2:3]
	s_andn2_b64 vcc, exec, s[96:97]
	s_cbranch_vccnz .LBB0_629
	s_cmp_eq_u32 s82, 0x100
	s_cbranch_scc0 .Lf4_done
	v_readlane_b32 s96, v254, 23
	v_readlane_b32 s97, v254, 24
	v_lshlrev_b32_e32 v64, 4, v212
	v_mov_b32_e32 v65, s84
	v_lshl_add_u32 v64, v65, 15, v64
	v_lshlrev_b32_e32 v65, 11, v65
	v_and_b32_e32 v60, 0x1e0, v212
	v_add_u32_e32 v65, v65, v60
	v_and_b32_e32 v60, 7, v212
	v_lshl_add_u32 v65, v60, 2, v65
	v_add_u32_e32 v65, 0xfd80000, v65
	s_nop 4
	v_mov_b32_e32 v62, v64
	global_load_dwordx4 v[20:23], v62, s[96:97] nt
	v_add_u32_e32 v62, 0x2000, v64
	global_load_dwordx4 v[24:27], v62, s[96:97] nt
	v_add_u32_e32 v62, 0x4000, v64
	global_load_dwordx4 v[28:31], v62, s[96:97] nt
	v_add_u32_e32 v62, 0x6000, v64
	global_load_dwordx4 v[32:35], v62, s[96:97] nt
	v_add_u32_e32 v62, 0x800000, v64
	global_load_dwordx4 v[36:39], v62, s[96:97] nt
	v_add_u32_e32 v62, 0x802000, v64
	global_load_dwordx4 v[40:43], v62, s[96:97] nt
	v_add_u32_e32 v62, 0x804000, v64
	global_load_dwordx4 v[44:47], v62, s[96:97] nt
	v_add_u32_e32 v62, 0x806000, v64
	global_load_dwordx4 v[48:51], v62, s[96:97] nt
	v_mov_b32_e32 v62, v65
	global_load_dword v52, v62, s[88:89]
	v_add_u32_e32 v62, 0x200, v65
	global_load_dword v53, v62, s[88:89]
	v_add_u32_e32 v62, 0x400, v65
	global_load_dword v54, v62, s[88:89]
	v_add_u32_e32 v62, 0x600, v65
	global_load_dword v55, v62, s[88:89]
	v_add_u32_e32 v62, 0x80000, v65
	global_load_dword v56, v62, s[88:89]
	v_add_u32_e32 v62, 0x80200, v65
	global_load_dword v57, v62, s[88:89]
	v_add_u32_e32 v62, 0x80400, v65
	global_load_dword v58, v62, s[88:89]
	v_add_u32_e32 v62, 0x80600, v65
	global_load_dword v59, v62, s[88:89]
	s_waitcnt vmcnt(0)
	v_add_f32_dpp v52, v52, v52 quad_perm:[1,0,3,2] row_mask:0xf bank_mask:0xf
	v_add_f32_dpp v53, v53, v53 quad_perm:[1,0,3,2] row_mask:0xf bank_mask:0xf
	v_add_f32_dpp v54, v54, v54 quad_perm:[1,0,3,2] row_mask:0xf bank_mask:0xf
	v_add_f32_dpp v55, v55, v55 quad_perm:[1,0,3,2] row_mask:0xf bank_mask:0xf
	v_add_f32_dpp v56, v56, v56 quad_perm:[1,0,3,2] row_mask:0xf bank_mask:0xf
	v_add_f32_dpp v57, v57, v57 quad_perm:[1,0,3,2] row_mask:0xf bank_mask:0xf
	v_add_f32_dpp v58, v58, v58 quad_perm:[1,0,3,2] row_mask:0xf bank_mask:0xf
	v_add_f32_dpp v59, v59, v59 quad_perm:[1,0,3,2] row_mask:0xf bank_mask:0xf
	v_add_f32_dpp v52, v52, v52 quad_perm:[2,3,0,1] row_mask:0xf bank_mask:0xf
	v_add_f32_dpp v53, v53, v53 quad_perm:[2,3,0,1] row_mask:0xf bank_mask:0xf
	v_add_f32_dpp v54, v54, v54 quad_perm:[2,3,0,1] row_mask:0xf bank_mask:0xf
	v_add_f32_dpp v55, v55, v55 quad_perm:[2,3,0,1] row_mask:0xf bank_mask:0xf
	v_add_f32_dpp v56, v56, v56 quad_perm:[2,3,0,1] row_mask:0xf bank_mask:0xf
	v_add_f32_dpp v57, v57, v57 quad_perm:[2,3,0,1] row_mask:0xf bank_mask:0xf
	v_add_f32_dpp v58, v58, v58 quad_perm:[2,3,0,1] row_mask:0xf bank_mask:0xf
	v_add_f32_dpp v59, v59, v59 quad_perm:[2,3,0,1] row_mask:0xf bank_mask:0xf
	v_add_f32_dpp v52, v52, v52 row_half_mirror row_mask:0xf bank_mask:0xf
	v_add_f32_dpp v53, v53, v53 row_half_mirror row_mask:0xf bank_mask:0xf
	v_add_f32_dpp v54, v54, v54 row_half_mirror row_mask:0xf bank_mask:0xf
	v_add_f32_dpp v55, v55, v55 row_half_mirror row_mask:0xf bank_mask:0xf
	v_add_f32_dpp v56, v56, v56 row_half_mirror row_mask:0xf bank_mask:0xf
	v_add_f32_dpp v57, v57, v57 row_half_mirror row_mask:0xf bank_mask:0xf
	v_add_f32_dpp v58, v58, v58 row_half_mirror row_mask:0xf bank_mask:0xf
	v_add_f32_dpp v59, v59, v59 row_half_mirror row_mask:0xf bank_mask:0xf
	v_mov_b32_e32 v60, 0x358637bd
	v_fmamk_f32 v52, v52, 0x3b800000, v60
	v_fmamk_f32 v53, v53, 0x3b800000, v60
	v_fmamk_f32 v54, v54, 0x3b800000, v60
	v_fmamk_f32 v55, v55, 0x3b800000, v60
	v_fmamk_f32 v56, v56, 0x3b800000, v60
	v_fmamk_f32 v57, v57, 0x3b800000, v60
	v_fmamk_f32 v58, v58, 0x3b800000, v60
	v_fmamk_f32 v59, v59, 0x3b800000, v60
	v_rsq_f32_e32 v52, v52
	v_rsq_f32_e32 v53, v53
	v_rsq_f32_e32 v54, v54
	v_rsq_f32_e32 v55, v55
	v_rsq_f32_e32 v56, v56
	v_rsq_f32_e32 v57, v57
	v_rsq_f32_e32 v58, v58
	v_rsq_f32_e32 v59, v59
	s_nop 0
	v_lshlrev_b32_e32 v62, 16, v20
	v_and_b32_e32 v63, 0xffff0000, v20
	v_mul_f32_e32 v62, v52, v62
	v_mul_f32_e32 v63, v52, v63
	v_cvt_pk_bf16_f32 v20, v62, v63
	v_lshlrev_b32_e32 v62, 16, v21
	v_and_b32_e32 v63, 0xffff0000, v21
	v_mul_f32_e32 v62, v52, v62
	v_mul_f32_e32 v63, v52, v63
	v_cvt_pk_bf16_f32 v21, v62, v63
	v_lshlrev_b32_e32 v62, 16, v22
	v_and_b32_e32 v63, 0xffff0000, v22
	v_mul_f32_e32 v62, v52, v62
	v_mul_f32_e32 v63, v52, v63
	v_cvt_pk_bf16_f32 v22, v62, v63
	v_lshlrev_b32_e32 v62, 16, v23
	v_and_b32_e32 v63, 0xffff0000, v23
	v_mul_f32_e32 v62, v52, v62
	v_mul_f32_e32 v63, v52, v63
	v_cvt_pk_bf16_f32 v23, v62, v63
	v_mov_b32_e32 v62, v64
	global_store_dwordx4 v62, v[20:23], s[96:97]
	v_lshlrev_b32_e32 v62, 16, v24
	v_and_b32_e32 v63, 0xffff0000, v24
	v_mul_f32_e32 v62, v53, v62
	v_mul_f32_e32 v63, v53, v63
	v_cvt_pk_bf16_f32 v24, v62, v63
	v_lshlrev_b32_e32 v62, 16, v25
	v_and_b32_e32 v63, 0xffff0000, v25
	v_mul_f32_e32 v62, v53, v62
; __device__ __forceinline__ void st_wt16(void* p, u32x4 v) { asm volatile("global_store_dwordx4 %0, %1, off sc1\n\ts_nop 1" : : "v"(p), "v"(v) : "memory"); }
; __device__ __forceinline__ void p5_fixup(const Params& p) {
;     ...
;         for (int u = 0; u < 4; ++u) { const int v = v0 + u * gsz; if (v < T_TOK * 128) {
;             const float ss = (s0[u].x + s0[u].y) + (s0[u].z + s0[u].w) + (s1[u].x + s1[u].y) + (s1[u].z + s1[u].w);
;             const float rstd = rsqrtf(ss * (1.0f / 256.0f) + EPS);
;             float f[8]; unpack8(hv[u], f);
; #pragma unroll
;             for (int e = 0; e < 8; ++e) f[e] *= rstd;
;             st_wt16(HM + (size_t)v * 8, pack8(f)); } }
	v_mul_f32_e32 v63, v53, v63
	v_cvt_pk_bf16_f32 v25, v62, v63
	v_lshlrev_b32_e32 v62, 16, v26
	v_and_b32_e32 v63, 0xffff0000, v26
	v_mul_f32_e32 v62, v53, v62
	v_mul_f32_e32 v63, v53, v63
	v_cvt_pk_bf16_f32 v26, v62, v63
	v_lshlrev_b32_e32 v62, 16, v27
	v_and_b32_e32 v63, 0xffff0000, v27
	v_mul_f32_e32 v62, v53, v62
	v_mul_f32_e32 v63, v53, v63
	v_cvt_pk_bf16_f32 v27, v62, v63
	v_add_u32_e32 v62, 0x2000, v64
	global_store_dwordx4 v62, v[24:27], s[96:97]
	v_lshlrev_b32_e32 v62, 16, v28
	v_and_b32_e32 v63, 0xffff0000, v28
	v_mul_f32_e32 v62, v54, v62
	v_mul_f32_e32 v63, v54, v63
	v_cvt_pk_bf16_f32 v28, v62, v63
	v_lshlrev_b32_e32 v62, 16, v29
	v_and_b32_e32 v63, 0xffff0000, v29
	v_mul_f32_e32 v62, v54, v62
	v_mul_f32_e32 v63, v54, v63
	v_cvt_pk_bf16_f32 v29, v62, v63
	v_lshlrev_b32_e32 v62, 16, v30
	v_and_b32_e32 v63, 0xffff0000, v30
	v_mul_f32_e32 v62, v54, v62
	v_mul_f32_e32 v63, v54, v63
	v_cvt_pk_bf16_f32 v30, v62, v63
	v_lshlrev_b32_e32 v62, 16, v31
	v_and_b32_e32 v63, 0xffff0000, v31
	v_mul_f32_e32 v62, v54, v62
	v_mul_f32_e32 v63, v54, v63
	v_cvt_pk_bf16_f32 v31, v62, v63
	v_add_u32_e32 v62, 0x4000, v64
	global_store_dwordx4 v62, v[28:31], s[96:97]
	v_lshlrev_b32_e32 v62, 16, v32
	v_and_b32_e32 v63, 0xffff0000, v32
	v_mul_f32_e32 v62, v55, v62
	v_mul_f32_e32 v63, v55, v63
	v_cvt_pk_bf16_f32 v32, v62, v63
	v_lshlrev_b32_e32 v62, 16, v33
	v_and_b32_e32 v63, 0xffff0000, v33
	v_mul_f32_e32 v62, v55, v62
	v_mul_f32_e32 v63, v55, v63
	v_cvt_pk_bf16_f32 v33, v62, v63
	v_lshlrev_b32_e32 v62, 16, v34
	v_and_b32_e32 v63, 0xffff0000, v34
	v_mul_f32_e32 v62, v55, v62
	v_mul_f32_e32 v63, v55, v63
	v_cvt_pk_bf16_f32 v34, v62, v63
	v_lshlrev_b32_e32 v62, 16, v35
	v_and_b32_e32 v63, 0xffff0000, v35
	v_mul_f32_e32 v62, v55, v62
	v_mul_f32_e32 v63, v55, v63
	v_cvt_pk_bf16_f32 v35, v62, v63
	v_add_u32_e32 v62, 0x6000, v64
	global_store_dwordx4 v62, v[32:35], s[96:97]
	v_lshlrev_b32_e32 v62, 16, v36
	v_and_b32_e32 v63, 0xffff0000, v36
	v_mul_f32_e32 v62, v56, v62
	v_mul_f32_e32 v63, v56, v63
	v_cvt_pk_bf16_f32 v36, v62, v63
	v_lshlrev_b32_e32 v62, 16, v37
	v_and_b32_e32 v63, 0xffff0000, v37
	v_mul_f32_e32 v62, v56, v62
	v_mul_f32_e32 v63, v56, v63
	v_cvt_pk_bf16_f32 v37, v62, v63
	v_lshlrev_b32_e32 v62, 16, v38
	v_and_b32_e32 v63, 0xffff0000, v38
	v_mul_f32_e32 v62, v56, v62
	v_mul_f32_e32 v63, v56, v63
	v_cvt_pk_bf16_f32 v38, v62, v63
	v_lshlrev_b32_e32 v62, 16, v39
	v_and_b32_e32 v63, 0xffff0000, v39
	v_mul_f32_e32 v62, v56, v62
	v_mul_f32_e32 v63, v56, v63
	v_cvt_pk_bf16_f32 v39, v62, v63
	v_add_u32_e32 v62, 0x800000, v64
	global_store_dwordx4 v62, v[36:39], s[96:97]
	v_lshlrev_b32_e32 v62, 16, v40
	v_and_b32_e32 v63, 0xffff0000, v40
	v_mul_f32_e32 v62, v57, v62
	v_mul_f32_e32 v63, v57, v63
	v_cvt_pk_bf16_f32 v40, v62, v63
	v_lshlrev_b32_e32 v62, 16, v41
	v_and_b32_e32 v63, 0xffff0000, v41
	v_mul_f32_e32 v62, v57, v62
	v_mul_f32_e32 v63, v57, v63
	v_cvt_pk_bf16_f32 v41, v62, v63
	v_lshlrev_b32_e32 v62, 16, v42
	v_and_b32_e32 v63, 0xffff0000, v42
	v_mul_f32_e32 v62, v57, v62
	v_mul_f32_e32 v63, v57, v63
	v_cvt_pk_bf16_f32 v42, v62, v63
	v_lshlrev_b32_e32 v62, 16, v43
	v_and_b32_e32 v63, 0xffff0000, v43
	v_mul_f32_e32 v62, v57, v62
	v_mul_f32_e32 v63, v57, v63
	v_cvt_pk_bf16_f32 v43, v62, v63
	v_add_u32_e32 v62, 0x802000, v64
	global_store_dwordx4 v62, v[40:43], s[96:97]
	v_lshlrev_b32_e32 v62, 16, v44
	v_and_b32_e32 v63, 0xffff0000, v44
	v_mul_f32_e32 v62, v58, v62
	v_mul_f32_e32 v63, v58, v63
	v_cvt_pk_bf16_f32 v44, v62, v63
	v_lshlrev_b32_e32 v62, 16, v45
	v_and_b32_e32 v63, 0xffff0000, v45
	v_mul_f32_e32 v62, v58, v62
	v_mul_f32_e32 v63, v58, v63
	v_cvt_pk_bf16_f32 v45, v62, v63
	v_lshlrev_b32_e32 v62, 16, v46
	v_and_b32_e32 v63, 0xffff0000, v46
	v_mul_f32_e32 v62, v58, v62
	v_mul_f32_e32 v63, v58, v63
	v_cvt_pk_bf16_f32 v46, v62, v63
	v_lshlrev_b32_e32 v62, 16, v47
	v_and_b32_e32 v63, 0xffff0000, v47
	v_mul_f32_e32 v62, v58, v62
	v_mul_f32_e32 v63, v58, v63
	v_cvt_pk_bf16_f32 v47, v62, v63
	v_add_u32_e32 v62, 0x804000, v64
	global_store_dwordx4 v62, v[44:47], s[96:97]
	v_lshlrev_b32_e32 v62, 16, v48
	v_and_b32_e32 v63, 0xffff0000, v48
	v_mul_f32_e32 v62, v59, v62
	v_mul_f32_e32 v63, v59, v63
	v_cvt_pk_bf16_f32 v48, v62, v63
	v_lshlrev_b32_e32 v62, 16, v49
	v_and_b32_e32 v63, 0xffff0000, v49
	v_mul_f32_e32 v62, v59, v62
	v_mul_f32_e32 v63, v59, v63
	v_cvt_pk_bf16_f32 v49, v62, v63
	v_lshlrev_b32_e32 v62, 16, v50
	v_and_b32_e32 v63, 0xffff0000, v50
	v_mul_f32_e32 v62, v59, v62
	v_mul_f32_e32 v63, v59, v63
	v_cvt_pk_bf16_f32 v50, v62, v63
	v_lshlrev_b32_e32 v62, 16, v51
	v_and_b32_e32 v63, 0xffff0000, v51
	v_mul_f32_e32 v62, v59, v62
	v_mul_f32_e32 v63, v59, v63
	v_cvt_pk_bf16_f32 v51, v62, v63
	v_add_u32_e32 v62, 0x806000, v64
	global_store_dwordx4 v62, v[48:51], s[96:97]
	s_nop 1
.Lf4_done:
	s_cmp_eq_u32 s101, 1
	s_cbranch_scc0 .Lw4_done
	s_mov_b32 s101, 0
	v_readfirstlane_b32 s96, v212
	s_nop 3
	s_cmp_lg_u32 s96, 0
	s_cbranch_scc1 .Lw4_bar
	v_readlane_b32 s96, v254, 3
	s_nop 3
	s_lshl_b32 s96, s96, 8
	v_mov_b32_e32 v250, 0xffc3500
	v_mov_b32_e32 v251, 0xffc2400
	v_add_u32_e32 v251, s96, v251
	s_mov_b32 s96, 0

; __device__ __forceinline__ void p5_fixup(const Params& p) {
;     ...
;     for (int v0 = gtid; v0 < T_TOK * 128; v0 += 4 * gsz) {
;         u32x4 hv[4]; float4 s0[4], s1[4];
; #pragma unroll
;         for (int u = 0; u < 4; ++u) { const int v = v0 + u * gsz; if (v < T_TOK * 128) { const int row = v >> 7, head = (v >> 5) & 3;
;             hv[u] = __builtin_nontemporal_load((const u32x4*)(HM + (size_t)v * 8)); s0[u] = *(const float4*)(SSQ + ((size_t)row * 4 + head) * 8); s1[u] = *(const float4*)(SSQ + ((size_t)row * 4 + head) * 8 + 4); } }
.Lprio5_done:
	s_movk_i32 s98, 0x64
	s_cmp_lg_u32 s82, 0x100
	s_cbranch_scc1 .Lhm_nofuse
	s_mov_b32 s98, 0
	s_mov_b32 s99, 1
	v_readlane_b32 s100, v254, 23
	v_readlane_b32 s101, v254, 24
	v_lshlrev_b32_e32 v250, 4, v212
	v_mov_b32_e32 v251, s84
	v_lshl_add_u32 v250, v251, 15, v250
	v_lshlrev_b32_e32 v251, 11, v251
	v_and_b32_e32 v252, 0x1e0, v212
	v_add_u32_e32 v251, v251, v252
	v_and_b32_e32 v252, 7, v212
	v_lshl_add_u32 v251, v252, 2, v251
	v_add_u32_e32 v251, 0xfe80000, v251
	v_add_u32_e32 v250, 0x1000000, v250

; __device__ __forceinline__ void p5_fixup(const Params& p) {
;     ...
;         for (int u = 0; u < 4; ++u) { const int v = v0 + u * gsz; if (v < T_TOK * 128) { const int row = v >> 7, head = (v >> 5) & 3;
;             hv[u] = __builtin_nontemporal_load((const u32x4*)(HM + (size_t)v * 8)); s0[u] = *(const float4*)(SSQ + ((size_t)row * 4 + head) * 8); s1[u] = *(const float4*)(SSQ + ((size_t)row * 4 + head) * 8 + 4); } }
.Lat_norope:
	s_or_b64 exec, exec, s[0:1]
	s_cmp_gt_u32 s98, 1
	s_cbranch_scc1 .Lhm_noissue
	v_mov_b32_e32 v252, s98
	v_lshl_add_u32 v255, v252, 23, v250
	v_lshl_add_u32 v252, v252, 19, v251
	global_load_dwordx4 v[230:233], v255, s[100:101] nt
	v_add_u32_e32 v255, 0x2000, v255
	global_load_dwordx4 v[234:237], v255, s[100:101] nt
	v_add_u32_e32 v255, 0x2000, v255
	global_load_dwordx4 v[238:241], v255, s[100:101] nt
	v_add_u32_e32 v255, 0x2000, v255
	global_load_dwordx4 v[242:245], v255, s[100:101] nt
	global_load_dword v246, v252, s[88:89]
	global_load_dword v247, v252, s[88:89] offset:512
	global_load_dword v248, v252, s[88:89] offset:1024
	global_load_dword v249, v252, s[88:89] offset:1536
	s_waitcnt vmcnt(8)
	s_branch .Lhm_issued

; __device__ __forceinline__ void st_wt16(void* p, u32x4 v) { asm volatile("global_store_dwordx4 %0, %1, off sc1\n\ts_nop 1" : : "v"(p), "v"(v) : "memory"); }
; __device__ __forceinline__ void p5_fixup(const Params& p) {
;     ...
;         for (int u = 0; u < 4; ++u) { const int v = v0 + u * gsz; if (v < T_TOK * 128) {
;             const float ss = (s0[u].x + s0[u].y) + (s0[u].z + s0[u].w) + (s1[u].x + s1[u].y) + (s1[u].z + s1[u].w);
;             const float rstd = rsqrtf(ss * (1.0f / 256.0f) + EPS);
;             float f[8]; unpack8(hv[u], f);
; #pragma unroll
;             for (int e = 0; e < 8; ++e) f[e] *= rstd;
;             st_wt16(HM + (size_t)v * 8, pack8(f)); } }
.Lattn_pf_done:
	s_cmp_gt_u32 s98, 1
	s_cbranch_scc1 .Lhm_noconsume
	v_add_f32_dpp v246, v246, v246 quad_perm:[1,0,3,2] row_mask:0xf bank_mask:0xf
	v_add_f32_dpp v247, v247, v247 quad_perm:[1,0,3,2] row_mask:0xf bank_mask:0xf
	v_add_f32_dpp v248, v248, v248 quad_perm:[1,0,3,2] row_mask:0xf bank_mask:0xf
	v_add_f32_dpp v249, v249, v249 quad_perm:[1,0,3,2] row_mask:0xf bank_mask:0xf
	v_add_f32_dpp v246, v246, v246 quad_perm:[2,3,0,1] row_mask:0xf bank_mask:0xf
	v_add_f32_dpp v247, v247, v247 quad_perm:[2,3,0,1] row_mask:0xf bank_mask:0xf
	v_add_f32_dpp v248, v248, v248 quad_perm:[2,3,0,1] row_mask:0xf bank_mask:0xf
	v_add_f32_dpp v249, v249, v249 quad_perm:[2,3,0,1] row_mask:0xf bank_mask:0xf
	v_add_f32_dpp v246, v246, v246 row_half_mirror row_mask:0xf bank_mask:0xf
	v_add_f32_dpp v247, v247, v247 row_half_mirror row_mask:0xf bank_mask:0xf
	v_add_f32_dpp v248, v248, v248 row_half_mirror row_mask:0xf bank_mask:0xf
	v_add_f32_dpp v249, v249, v249 row_half_mirror row_mask:0xf bank_mask:0xf
	v_mov_b32_e32 v252, 0x358637bd
	v_mov_b32_e32 v255, s98
	v_fmamk_f32 v246, v246, 0x3b800000, v252
	v_fmamk_f32 v247, v247, 0x3b800000, v252
	v_fmamk_f32 v248, v248, 0x3b800000, v252
	v_fmamk_f32 v249, v249, 0x3b800000, v252
	v_rsq_f32_e32 v246, v246
	v_rsq_f32_e32 v247, v247
	v_rsq_f32_e32 v248, v248
	v_rsq_f32_e32 v249, v249
	v_lshl_add_u32 v255, v255, 23, v250
	v_lshlrev_b32_e32 v252, 16, v230
	v_and_b32_e32 v253, 0xffff0000, v230
	v_mul_f32_e32 v252, v246, v252
	v_mul_f32_e32 v253, v246, v253
	v_cvt_pk_bf16_f32 v230, v252, v253
	v_lshlrev_b32_e32 v252, 16, v231
	v_and_b32_e32 v253, 0xffff0000, v231
	v_mul_f32_e32 v252, v246, v252
	v_mul_f32_e32 v253, v246, v253
	v_cvt_pk_bf16_f32 v231, v252, v253
	v_lshlrev_b32_e32 v252, 16, v232
	v_and_b32_e32 v253, 0xffff0000, v232
	v_mul_f32_e32 v252, v246, v252
	v_mul_f32_e32 v253, v246, v253
	v_cvt_pk_bf16_f32 v232, v252, v253
	v_lshlrev_b32_e32 v252, 16, v233
	v_and_b32_e32 v253, 0xffff0000, v233
	v_mul_f32_e32 v252, v246, v252
	v_mul_f32_e32 v253, v246, v253
	v_cvt_pk_bf16_f32 v233, v252, v253
	global_store_dwordx4 v255, v[230:233], s[100:101]
	v_add_u32_e32 v255, 0x2000, v255
	v_lshlrev_b32_e32 v252, 16, v234
	v_and_b32_e32 v253, 0xffff0000, v234
	v_mul_f32_e32 v252, v247, v252
	v_mul_f32_e32 v253, v247, v253
	v_cvt_pk_bf16_f32 v234, v252, v253
	v_lshlrev_b32_e32 v252, 16, v235
	v_and_b32_e32 v253, 0xffff0000, v235
	v_mul_f32_e32 v252, v247, v252
	v_mul_f32_e32 v253, v247, v253
	v_cvt_pk_bf16_f32 v235, v252, v253
	v_lshlrev_b32_e32 v252, 16, v236
	v_and_b32_e32 v253, 0xffff0000, v236
	v_mul_f32_e32 v252, v247, v252
	v_mul_f32_e32 v253, v247, v253
	v_cvt_pk_bf16_f32 v236, v252, v253
	v_lshlrev_b32_e32 v252, 16, v237
	v_and_b32_e32 v253, 0xffff0000, v237
	v_mul_f32_e32 v252, v247, v252
	v_mul_f32_e32 v253, v247, v253
	v_cvt_pk_bf16_f32 v237, v252, v253
	global_store_dwordx4 v255, v[234:237], s[100:101]
	v_add_u32_e32 v255, 0x2000, v255
	v_lshlrev_b32_e32 v252, 16, v238
	v_and_b32_e32 v253, 0xffff0000, v238
	v_mul_f32_e32 v252, v248, v252
	v_mul_f32_e32 v253, v248, v253
	v_cvt_pk_bf16_f32 v238, v252, v253
	v_lshlrev_b32_e32 v252, 16, v239
	v_and_b32_e32 v253, 0xffff0000, v239
	v_mul_f32_e32 v252, v248, v252
	v_mul_f32_e32 v253, v248, v253
	v_cvt_pk_bf16_f32 v239, v252, v253
	v_lshlrev_b32_e32 v252, 16, v240
	v_and_b32_e32 v253, 0xffff0000, v240
	v_mul_f32_e32 v252, v248, v252
	v_mul_f32_e32 v253, v248, v253
	v_cvt_pk_bf16_f32 v240, v252, v253
	v_lshlrev_b32_e32 v252, 16, v241
	v_and_b32_e32 v253, 0xffff0000, v241
	v_mul_f32_e32 v252, v248, v252
	v_mul_f32_e32 v253, v248, v253
	v_cvt_pk_bf16_f32 v241, v252, v253
	global_store_dwordx4 v255, v[238:241], s[100:101]
	v_add_u32_e32 v255, 0x2000, v255
	v_lshlrev_b32_e32 v252, 16, v242
	v_and_b32_e32 v253, 0xffff0000, v242
	v_mul_f32_e32 v252, v249, v252
	v_mul_f32_e32 v253, v249, v253
	v_cvt_pk_bf16_f32 v242, v252, v253
	v_lshlrev_b32_e32 v252, 16, v243
	v_and_b32_e32 v253, 0xffff0000, v243
	v_mul_f32_e32 v252, v249, v252
	v_mul_f32_e32 v253, v249, v253
	v_cvt_pk_bf16_f32 v243, v252, v253
	v_lshlrev_b32_e32 v252, 16, v244
	v_and_b32_e32 v253, 0xffff0000, v244
	v_mul_f32_e32 v252, v249, v252
	v_mul_f32_e32 v253, v249, v253
	v_cvt_pk_bf16_f32 v244, v252, v253
	v_lshlrev_b32_e32 v252, 16, v245
	v_and_b32_e32 v253, 0xffff0000, v245
	v_mul_f32_e32 v252, v249, v252
	v_mul_f32_e32 v253, v249, v253
	v_cvt_pk_bf16_f32 v245, v252, v253
	global_store_dwordx4 v255, v[242:245], s[100:101]
	s_nop 1
